# in_proj gate tiles: dedicated straight-line packed-f32 sigmoid/u8 epilogue (no per-group branches), on top of merge rescale epilogue
# baseline (speedup 1.0000x reference)
;     __device__ __forceinline__ void operator()(Acc& acc, const Unit& u, int wr, int wc, int fr, int fq) const {
;         const int rowb = u.pm * BM + wr * 64 + fr, colb = u.pn * BM + wc * 64 + 8 * fq;
;         bf16* base; int sA, sM2, sM1; bool sig = false;
;         if (u.pn < 12) { base = qkv + (size_t)rowb * 3072 + colb; sA = 128 * 3072; sM2 = 32 * 3072; sM1 = 16 * 3072; }
;         else if (u.pn < 14) { const int ch = colb - 3072, gg = ch >> 4, c = ch & 15;
;             base = a2 + ((size_t)(gg * ROWS_G + u.pm * 8 + wr * 2) * K2 + fr * 16 + c); sA = 4 * K2; sM2 = K2; sM1 = 256; }
;         else if (u.pn < 16) { base = qm + (size_t)rowb * 512 + (colb - 3584); sA = 128 * 512; sM2 = 32 * 512; sM1 = 16 * 512; }
;         else { base = (bf16*)(gates + (size_t)rowb * 6144 + (colb - 4096)); sA = 64 * 6144; sM2 = 16 * 6144; sM1 = 8 * 6144; sig = true; }
;         const int sB = (u.pn >= 12 && u.pn < 14) ? 2 * ROWS_G * K2 : (u.pn >= 16 ? BJ / 2 : BJ);
.LBB0_262:
	s_cmp_gt_i32 s10, 15
	s_cbranch_scc1 .Lipg
	v_readlane_b32 s46, v254, 18
	v_lshl_add_u32 v42, s43, 8, v174
	v_lshl_or_b32 v98, s10, 8, v176
	s_cmp_gt_i32 s10, 11
	s_mov_b64 s[28:29], -1
	v_readlane_b32 s47, v254, 19
	s_cbranch_scc0 .LBB0_271
	s_cmp_gt_u32 s10, 13
	s_cbranch_scc0 .LBB0_268
	s_cmp_gt_u32 s10, 15
	v_ashrrev_i32_e32 v43, 31, v42
	s_mov_b64 s[26:27], -1
	s_mov_b64 s[2:3], -1
	s_cbranch_scc0 .LBB0_266
	v_mov_b64_e32 v[44:45], s[50:51]
	v_mad_i64_i32 v[44:45], s[2:3], v42, s49, v[44:45]
	s_movk_i32 s2, 0xf000
	v_lshl_add_u64 v[44:45], v[44:45], 0, v[98:99]
	s_mov_b32 s3, -1
	v_lshl_add_u64 v[172:173], v[44:45], 0, s[2:3]
	s_mov_b64 s[2:3], 0

; __device__ __forceinline__ u32x4 pack8(f32x4 a, f32x4 b) { u32x4 w; w.x = cvt_pk_bf16(a[0], a[1]); w.y = cvt_pk_bf16(a[2], a[3]); w.z = cvt_pk_bf16(b[0], b[1]); w.w = cvt_pk_bf16(b[2], b[3]); return w; }
; __device__ __forceinline__ float fast_sigmoid(float v) { return __builtin_amdgcn_rcpf(1.0f + __builtin_amdgcn_exp2f(-v * LOG2E)); }
;     w = __builtin_amdgcn_cvt_pk_u8_f32(g[2] * 256.0f - 0.5f, 2, w); w = __builtin_amdgcn_cvt_pk_u8_f32(g[3] * 256.0f - 0.5f, 3, w); return w; }
;     __device__ __forceinline__ void operator()(Acc& acc, const Unit& u, int wr, int wc, int fr, int fq) const {
;     ...
;         else { base = (bf16*)(gates + (size_t)rowb * 6144 + (colb - 4096)); sA = 64 * 6144; sM2 = 16 * 6144; sM1 = 8 * 6144; sig = true; }
;         const int sB = (u.pn >= 12 && u.pn < 14) ? 2 * ROWS_G * K2 : (u.pn >= 16 ? BJ / 2 : BJ);
;         f32x4 bv[2][2];
; #pragma unroll
;         for (int bj = 0; bj < 2; ++bj)
; #pragma unroll
;             for (int n = 0; n < 2; ++n) bv[bj][n] = *(const f32x4*)(bias + colb + bj * BJ + 4 * n);
; #pragma unroll
;         for (int ai = 0; ai < 2; ++ai)
; #pragma unroll
;             for (int m = 0; m < 4; ++m) { bf16* rowp = base + (size_t)ai * sA + (size_t)(m >> 1) * sM2 + (size_t)(m & 1) * sM1;
; #pragma unroll
;                 for (int bj = 0; bj < 2; ++bj) { f32x4 v0 = acc[ai][bj][m][0] + bv[bj][0], v1 = acc[ai][bj][m][1] + bv[bj][1];
;                     if (sig) {
; #pragma unroll
;                         for (int e = 0; e < 4; ++e) { v0[e] = fast_sigmoid(v0[e]); v1[e] = fast_sigmoid(v1[e]); }
;                         *(u32x2*)(rowp + (size_t)bj * sB) = (u32x2){pack_gate4(v0), pack_gate4(v1)}; }
;                     else *(u32x4*)(rowp + (size_t)bj * sB) = pack8(v0, v1); } }
.Lipg:
	v_readlane_b32 s46, v254, 18
	v_readlane_b32 s47, v254, 19
	s_mov_b32 s57, 0xfffe
	s_and_b64 vcc, exec, s[0:1]
	s_cbranch_vccz .Lipg_nopref
	v_lshl_or_b32 v210, s14, 8, v176
	v_mov_b32_e32 v211, 0
	v_lshl_add_u64 v[210:211], v[210:211], 2, s[8:9]
	global_load_dwordx4 v[194:197], v[210:211], off
	global_load_dwordx4 v[198:201], v[210:211], off offset:16
	global_load_dwordx4 v[202:205], v[210:211], off offset:128
	global_load_dwordx4 v[206:209], v[210:211], off offset:144
.Lipg_nopref:
	v_lshl_add_u32 v178, s43, 8, v174
	v_lshl_or_b32 v180, s10, 8, v176
	v_mov_b32_e32 v181, 0
	v_mov_b64_e32 v[182:183], s[50:51]
	v_mad_i64_i32 v[182:183], s[2:3], v178, s49, v[182:183]
	s_movk_i32 s2, 0xf000
	v_lshl_add_u64 v[182:183], v[182:183], 0, v[180:181]
	s_mov_b32 s3, -1
	v_lshl_add_u64 v[172:173], v[182:183], 0, s[2:3]
	s_mov_b32 s100, 0xbfb8aa3b
	s_mov_b32 s101, 0xbfb8aa3b
	s_mov_b32 s22, 1.0
	s_mov_b32 s23, 1.0
	s_mov_b32 s24, s72
	s_mov_b32 s25, s72
	v_mov_b32_e32 v212, -0.5
	v_mov_b32_e32 v213, -0.5
	s_mov_b32 s27, 0
	v_pk_mul_f32 v[144:145], v[144:145], s[100:101]
	v_pk_mul_f32 v[146:147], v[146:147], s[100:101]
	v_pk_mul_f32 v[140:141], v[140:141], s[100:101]
	v_pk_mul_f32 v[142:143], v[142:143], s[100:101]
	v_exp_f32_e32 v144, v144
	v_exp_f32_e32 v145, v145
	v_exp_f32_e32 v146, v146
	v_exp_f32_e32 v147, v147
	v_exp_f32_e32 v140, v140
	v_exp_f32_e32 v141, v141
	v_exp_f32_e32 v142, v142
	v_exp_f32_e32 v143, v143
	v_pk_add_f32 v[144:145], v[144:145], s[22:23]
	v_pk_add_f32 v[146:147], v[146:147], s[22:23]
	v_pk_add_f32 v[140:141], v[140:141], s[22:23]
	v_pk_add_f32 v[142:143], v[142:143], s[22:23]
	v_rcp_f32_e32 v144, v144
	v_rcp_f32_e32 v145, v145
	v_rcp_f32_e32 v146, v146
	v_rcp_f32_e32 v147, v147
	v_rcp_f32_e32 v140, v140
	v_rcp_f32_e32 v141, v141
	v_rcp_f32_e32 v142, v142
	v_rcp_f32_e32 v143, v143
	v_pk_fma_f32 v[144:145], v[144:145], s[24:25], v[212:213]
	v_pk_fma_f32 v[146:147], v[146:147], s[24:25], v[212:213]
	v_pk_fma_f32 v[140:141], v[140:141], s[24:25], v[212:213]
	v_pk_fma_f32 v[142:143], v[142:143], s[24:25], v[212:213]
	v_cvt_pk_u8_f32 v186, v144, 0, 0
	v_cvt_pk_u8_f32 v186, v145, 1, v186
	v_cvt_pk_u8_f32 v186, v146, 2, v186
	v_cvt_pk_u8_f32 v186, v147, 3, v186
	v_cvt_pk_u8_f32 v187, v140, 0, 0
	v_cvt_pk_u8_f32 v187, v141, 1, v187
	v_cvt_pk_u8_f32 v187, v142, 2, v187
	v_cvt_pk_u8_f32 v187, v143, 3, v187
	global_store_dwordx2 v[172:173], v[186:187], off
	v_pk_mul_f32 v[136:137], v[136:137], s[100:101]
	v_pk_mul_f32 v[138:139], v[138:139], s[100:101]
	v_pk_mul_f32 v[132:133], v[132:133], s[100:101]
	v_pk_mul_f32 v[134:135], v[134:135], s[100:101]
	v_exp_f32_e32 v136, v136
	v_exp_f32_e32 v137, v137
	v_exp_f32_e32 v138, v138
	v_exp_f32_e32 v139, v139
	v_exp_f32_e32 v132, v132
	v_exp_f32_e32 v133, v133
	v_exp_f32_e32 v134, v134
	v_exp_f32_e32 v135, v135
	v_pk_add_f32 v[136:137], v[136:137], s[22:23]
	v_pk_add_f32 v[138:139], v[138:139], s[22:23]
	v_pk_add_f32 v[132:133], v[132:133], s[22:23]
	v_pk_add_f32 v[134:135], v[134:135], s[22:23]
	v_rcp_f32_e32 v136, v136
	v_rcp_f32_e32 v137, v137
	v_rcp_f32_e32 v138, v138
	v_rcp_f32_e32 v139, v139
	v_rcp_f32_e32 v132, v132
	v_rcp_f32_e32 v133, v133
	v_rcp_f32_e32 v134, v134
	v_rcp_f32_e32 v135, v135
	v_pk_fma_f32 v[136:137], v[136:137], s[24:25], v[212:213]
	v_pk_fma_f32 v[138:139], v[138:139], s[24:25], v[212:213]
	v_pk_fma_f32 v[132:133], v[132:133], s[24:25], v[212:213]
	v_pk_fma_f32 v[134:135], v[134:135], s[24:25], v[212:213]
	v_cvt_pk_u8_f32 v188, v136, 0, 0
	v_cvt_pk_u8_f32 v188, v137, 1, v188
	v_cvt_pk_u8_f32 v188, v138, 2, v188
	v_cvt_pk_u8_f32 v188, v139, 3, v188
	v_cvt_pk_u8_f32 v189, v132, 0, 0
	v_cvt_pk_u8_f32 v189, v133, 1, v189
	v_cvt_pk_u8_f32 v189, v134, 2, v189
	v_cvt_pk_u8_f32 v189, v135, 3, v189
	global_store_dwordx2 v[172:173], v[188:189], off offset:32
	s_mov_b32 s26, 0x18000
	v_lshl_add_u64 v[184:185], v[172:173], 0, s[26:27]
	v_pk_mul_f32 v[128:129], v[128:129], s[100:101]
	v_pk_mul_f32 v[130:131], v[130:131], s[100:101]
	v_pk_mul_f32 v[124:125], v[124:125], s[100:101]
	v_pk_mul_f32 v[126:127], v[126:127], s[100:101]
	v_exp_f32_e32 v128, v128
	v_exp_f32_e32 v129, v129
	v_exp_f32_e32 v130, v130
	v_exp_f32_e32 v131, v131
	v_exp_f32_e32 v124, v124
	v_exp_f32_e32 v125, v125
	v_exp_f32_e32 v126, v126
	v_exp_f32_e32 v127, v127
	v_pk_add_f32 v[128:129], v[128:129], s[22:23]
	v_pk_add_f32 v[130:131], v[130:131], s[22:23]
	v_pk_add_f32 v[124:125], v[124:125], s[22:23]
	v_pk_add_f32 v[126:127], v[126:127], s[22:23]
	v_rcp_f32_e32 v128, v128
	v_rcp_f32_e32 v129, v129
	v_rcp_f32_e32 v130, v130
	v_rcp_f32_e32 v131, v131
	v_rcp_f32_e32 v124, v124
	v_rcp_f32_e32 v125, v125
	v_rcp_f32_e32 v126, v126
	v_rcp_f32_e32 v127, v127
	v_pk_fma_f32 v[128:129], v[128:129], s[24:25], v[212:213]
	v_pk_fma_f32 v[130:131], v[130:131], s[24:25], v[212:213]
	v_pk_fma_f32 v[124:125], v[124:125], s[24:25], v[212:213]
	v_pk_fma_f32 v[126:127], v[126:127], s[24:25], v[212:213]
	v_cvt_pk_u8_f32 v186, v128, 0, 0
	v_cvt_pk_u8_f32 v186, v129, 1, v186
	v_cvt_pk_u8_f32 v186, v130, 2, v186
	v_cvt_pk_u8_f32 v186, v131, 3, v186
	v_cvt_pk_u8_f32 v187, v124, 0, 0
	v_cvt_pk_u8_f32 v187, v125, 1, v187
	v_cvt_pk_u8_f32 v187, v126, 2, v187
	v_cvt_pk_u8_f32 v187, v127, 3, v187
	global_store_dwordx2 v[184:185], v[186:187], off
	v_pk_mul_f32 v[120:121], v[120:121], s[100:101]
	v_pk_mul_f32 v[122:123], v[122:123], s[100:101]
	v_pk_mul_f32 v[116:117], v[116:117], s[100:101]
	v_pk_mul_f32 v[118:119], v[118:119], s[100:101]
	v_exp_f32_e32 v120, v120
	v_exp_f32_e32 v121, v121
	v_exp_f32_e32 v122, v122
	v_exp_f32_e32 v123, v123
	v_exp_f32_e32 v116, v116
	v_exp_f32_e32 v117, v117
	v_exp_f32_e32 v118, v118
	v_exp_f32_e32 v119, v119
; __device__ __forceinline__ float fast_sigmoid(float v) { return __builtin_amdgcn_rcpf(1.0f + __builtin_amdgcn_exp2f(-v * LOG2E)); }
;     w = __builtin_amdgcn_cvt_pk_u8_f32(g[2] * 256.0f - 0.5f, 2, w); w = __builtin_amdgcn_cvt_pk_u8_f32(g[3] * 256.0f - 0.5f, 3, w); return w; }
;     __device__ __forceinline__ void operator()(Acc& acc, const Unit& u, int wr, int wc, int fr, int fq) const {
;     ...
;                     if (sig) {
; #pragma unroll
;                         for (int e = 0; e < 4; ++e) { v0[e] = fast_sigmoid(v0[e]); v1[e] = fast_sigmoid(v1[e]); }
;                         *(u32x2*)(rowp + (size_t)bj * sB) = (u32x2){pack_gate4(v0), pack_gate4(v1)}; }
	v_pk_add_f32 v[120:121], v[120:121], s[22:23]
	v_pk_add_f32 v[122:123], v[122:123], s[22:23]
	v_pk_add_f32 v[116:117], v[116:117], s[22:23]
	v_pk_add_f32 v[118:119], v[118:119], s[22:23]
	v_rcp_f32_e32 v120, v120
	v_rcp_f32_e32 v121, v121
	v_rcp_f32_e32 v122, v122
	v_rcp_f32_e32 v123, v123
	v_rcp_f32_e32 v116, v116
	v_rcp_f32_e32 v117, v117
	v_rcp_f32_e32 v118, v118
	v_rcp_f32_e32 v119, v119
	v_pk_fma_f32 v[120:121], v[120:121], s[24:25], v[212:213]
	v_pk_fma_f32 v[122:123], v[122:123], s[24:25], v[212:213]
	v_pk_fma_f32 v[116:117], v[116:117], s[24:25], v[212:213]
	v_pk_fma_f32 v[118:119], v[118:119], s[24:25], v[212:213]
	v_cvt_pk_u8_f32 v188, v120, 0, 0
	v_cvt_pk_u8_f32 v188, v121, 1, v188
	v_cvt_pk_u8_f32 v188, v122, 2, v188
	v_cvt_pk_u8_f32 v188, v123, 3, v188
	v_cvt_pk_u8_f32 v189, v116, 0, 0
	v_cvt_pk_u8_f32 v189, v117, 1, v189
	v_cvt_pk_u8_f32 v189, v118, 2, v189
	v_cvt_pk_u8_f32 v189, v119, 3, v189
	global_store_dwordx2 v[184:185], v[188:189], off offset:32
	v_lshl_add_u64 v[184:185], v[184:185], 0, s[26:27]
	v_pk_mul_f32 v[112:113], v[112:113], s[100:101]
	v_pk_mul_f32 v[114:115], v[114:115], s[100:101]
	v_pk_mul_f32 v[108:109], v[108:109], s[100:101]
	v_pk_mul_f32 v[110:111], v[110:111], s[100:101]
	v_exp_f32_e32 v112, v112
	v_exp_f32_e32 v113, v113
	v_exp_f32_e32 v114, v114
	v_exp_f32_e32 v115, v115
	v_exp_f32_e32 v108, v108
	v_exp_f32_e32 v109, v109
	v_exp_f32_e32 v110, v110
	v_exp_f32_e32 v111, v111
	v_pk_add_f32 v[112:113], v[112:113], s[22:23]
	v_pk_add_f32 v[114:115], v[114:115], s[22:23]
	v_pk_add_f32 v[108:109], v[108:109], s[22:23]
	v_pk_add_f32 v[110:111], v[110:111], s[22:23]
	v_rcp_f32_e32 v112, v112
	v_rcp_f32_e32 v113, v113
	v_rcp_f32_e32 v114, v114
	v_rcp_f32_e32 v115, v115
	v_rcp_f32_e32 v108, v108
	v_rcp_f32_e32 v109, v109
	v_rcp_f32_e32 v110, v110
	v_rcp_f32_e32 v111, v111
	v_pk_fma_f32 v[112:113], v[112:113], s[24:25], v[212:213]
	v_pk_fma_f32 v[114:115], v[114:115], s[24:25], v[212:213]
	v_pk_fma_f32 v[108:109], v[108:109], s[24:25], v[212:213]
	v_pk_fma_f32 v[110:111], v[110:111], s[24:25], v[212:213]
	v_cvt_pk_u8_f32 v186, v112, 0, 0
	v_cvt_pk_u8_f32 v186, v113, 1, v186
	v_cvt_pk_u8_f32 v186, v114, 2, v186
	v_cvt_pk_u8_f32 v186, v115, 3, v186
	v_cvt_pk_u8_f32 v187, v108, 0, 0
	v_cvt_pk_u8_f32 v187, v109, 1, v187
	v_cvt_pk_u8_f32 v187, v110, 2, v187
	v_cvt_pk_u8_f32 v187, v111, 3, v187
	global_store_dwordx2 v[184:185], v[186:187], off
	v_pk_mul_f32 v[104:105], v[104:105], s[100:101]
	v_pk_mul_f32 v[106:107], v[106:107], s[100:101]
	v_pk_mul_f32 v[100:101], v[100:101], s[100:101]
	v_pk_mul_f32 v[102:103], v[102:103], s[100:101]
	v_exp_f32_e32 v104, v104
	v_exp_f32_e32 v105, v105
	v_exp_f32_e32 v106, v106
	v_exp_f32_e32 v107, v107
	v_exp_f32_e32 v100, v100
	v_exp_f32_e32 v101, v101
	v_exp_f32_e32 v102, v102
	v_exp_f32_e32 v103, v103
	v_pk_add_f32 v[104:105], v[104:105], s[22:23]
	v_pk_add_f32 v[106:107], v[106:107], s[22:23]
	v_pk_add_f32 v[100:101], v[100:101], s[22:23]
	v_pk_add_f32 v[102:103], v[102:103], s[22:23]
	v_rcp_f32_e32 v104, v104
	v_rcp_f32_e32 v105, v105
	v_rcp_f32_e32 v106, v106
	v_rcp_f32_e32 v107, v107
	v_rcp_f32_e32 v100, v100
	v_rcp_f32_e32 v101, v101
	v_rcp_f32_e32 v102, v102
	v_rcp_f32_e32 v103, v103
	v_pk_fma_f32 v[104:105], v[104:105], s[24:25], v[212:213]
	v_pk_fma_f32 v[106:107], v[106:107], s[24:25], v[212:213]
	v_pk_fma_f32 v[100:101], v[100:101], s[24:25], v[212:213]
	v_pk_fma_f32 v[102:103], v[102:103], s[24:25], v[212:213]
	v_cvt_pk_u8_f32 v188, v104, 0, 0
	v_cvt_pk_u8_f32 v188, v105, 1, v188
	v_cvt_pk_u8_f32 v188, v106, 2, v188
	v_cvt_pk_u8_f32 v188, v107, 3, v188
	v_cvt_pk_u8_f32 v189, v100, 0, 0
	v_cvt_pk_u8_f32 v189, v101, 1, v189
	v_cvt_pk_u8_f32 v189, v102, 2, v189
	v_cvt_pk_u8_f32 v189, v103, 3, v189
	global_store_dwordx2 v[184:185], v[188:189], off offset:32
	v_lshl_add_u64 v[184:185], v[184:185], 0, s[26:27]
	v_pk_mul_f32 v[94:95], v[94:95], s[100:101]
	v_pk_mul_f32 v[96:97], v[96:97], s[100:101]
	v_pk_mul_f32 v[90:91], v[90:91], s[100:101]
	v_pk_mul_f32 v[92:93], v[92:93], s[100:101]
	v_exp_f32_e32 v94, v94
	v_exp_f32_e32 v95, v95
	v_exp_f32_e32 v96, v96
	v_exp_f32_e32 v97, v97
	v_exp_f32_e32 v90, v90
	v_exp_f32_e32 v91, v91
	v_exp_f32_e32 v92, v92
	v_exp_f32_e32 v93, v93
	v_pk_add_f32 v[94:95], v[94:95], s[22:23]
	v_pk_add_f32 v[96:97], v[96:97], s[22:23]
	v_pk_add_f32 v[90:91], v[90:91], s[22:23]
	v_pk_add_f32 v[92:93], v[92:93], s[22:23]
	v_rcp_f32_e32 v94, v94
	v_rcp_f32_e32 v95, v95
	v_rcp_f32_e32 v96, v96
	v_rcp_f32_e32 v97, v97
	v_rcp_f32_e32 v90, v90
	v_rcp_f32_e32 v91, v91
	v_rcp_f32_e32 v92, v92
	v_rcp_f32_e32 v93, v93
	v_pk_fma_f32 v[94:95], v[94:95], s[24:25], v[212:213]
	v_pk_fma_f32 v[96:97], v[96:97], s[24:25], v[212:213]
	v_pk_fma_f32 v[90:91], v[90:91], s[24:25], v[212:213]
	v_pk_fma_f32 v[92:93], v[92:93], s[24:25], v[212:213]
	v_cvt_pk_u8_f32 v186, v94, 0, 0
	v_cvt_pk_u8_f32 v186, v95, 1, v186
	v_cvt_pk_u8_f32 v186, v96, 2, v186
	v_cvt_pk_u8_f32 v186, v97, 3, v186
	v_cvt_pk_u8_f32 v187, v90, 0, 0
	v_cvt_pk_u8_f32 v187, v91, 1, v187
	v_cvt_pk_u8_f32 v187, v92, 2, v187
	v_cvt_pk_u8_f32 v187, v93, 3, v187
	global_store_dwordx2 v[184:185], v[186:187], off
	v_pk_mul_f32 v[86:87], v[86:87], s[100:101]
	v_pk_mul_f32 v[88:89], v[88:89], s[100:101]
	v_pk_mul_f32 v[82:83], v[82:83], s[100:101]
	v_pk_mul_f32 v[84:85], v[84:85], s[100:101]
	v_exp_f32_e32 v86, v86
	v_exp_f32_e32 v87, v87
	v_exp_f32_e32 v88, v88
	v_exp_f32_e32 v89, v89
	v_exp_f32_e32 v82, v82
	v_exp_f32_e32 v83, v83
	v_exp_f32_e32 v84, v84
	v_exp_f32_e32 v85, v85
	v_pk_add_f32 v[86:87], v[86:87], s[22:23]
	v_pk_add_f32 v[88:89], v[88:89], s[22:23]
	v_pk_add_f32 v[82:83], v[82:83], s[22:23]
; __device__ __forceinline__ float fast_sigmoid(float v) { return __builtin_amdgcn_rcpf(1.0f + __builtin_amdgcn_exp2f(-v * LOG2E)); }
;     w = __builtin_amdgcn_cvt_pk_u8_f32(g[2] * 256.0f - 0.5f, 2, w); w = __builtin_amdgcn_cvt_pk_u8_f32(g[3] * 256.0f - 0.5f, 3, w); return w; }
;     __device__ __forceinline__ void operator()(Acc& acc, const Unit& u, int wr, int wc, int fr, int fq) const {
;     ...
;                     if (sig) {
; #pragma unroll
;                         for (int e = 0; e < 4; ++e) { v0[e] = fast_sigmoid(v0[e]); v1[e] = fast_sigmoid(v1[e]); }
;                         *(u32x2*)(rowp + (size_t)bj * sB) = (u32x2){pack_gate4(v0), pack_gate4(v1)}; }
	v_pk_add_f32 v[84:85], v[84:85], s[22:23]
	v_rcp_f32_e32 v86, v86
	v_rcp_f32_e32 v87, v87
	v_rcp_f32_e32 v88, v88
	v_rcp_f32_e32 v89, v89
	v_rcp_f32_e32 v82, v82
	v_rcp_f32_e32 v83, v83
	v_rcp_f32_e32 v84, v84
	v_rcp_f32_e32 v85, v85
	v_pk_fma_f32 v[86:87], v[86:87], s[24:25], v[212:213]
	v_pk_fma_f32 v[88:89], v[88:89], s[24:25], v[212:213]
	v_pk_fma_f32 v[82:83], v[82:83], s[24:25], v[212:213]
	v_pk_fma_f32 v[84:85], v[84:85], s[24:25], v[212:213]
	v_cvt_pk_u8_f32 v188, v86, 0, 0
	v_cvt_pk_u8_f32 v188, v87, 1, v188
	v_cvt_pk_u8_f32 v188, v88, 2, v188
	v_cvt_pk_u8_f32 v188, v89, 3, v188
	v_cvt_pk_u8_f32 v189, v82, 0, 0
	v_cvt_pk_u8_f32 v189, v83, 1, v189
	v_cvt_pk_u8_f32 v189, v84, 2, v189
	v_cvt_pk_u8_f32 v189, v85, 3, v189
	global_store_dwordx2 v[184:185], v[188:189], off offset:32
	s_mov_b32 s26, 0x78000
	v_lshl_add_u64 v[184:185], v[184:185], 0, s[26:27]
	v_pk_mul_f32 v[78:79], v[78:79], s[100:101]
	v_pk_mul_f32 v[80:81], v[80:81], s[100:101]
	v_pk_mul_f32 v[74:75], v[74:75], s[100:101]
	v_pk_mul_f32 v[76:77], v[76:77], s[100:101]
	v_exp_f32_e32 v78, v78
	v_exp_f32_e32 v79, v79
	v_exp_f32_e32 v80, v80
	v_exp_f32_e32 v81, v81
	v_exp_f32_e32 v74, v74
	v_exp_f32_e32 v75, v75
	v_exp_f32_e32 v76, v76
	v_exp_f32_e32 v77, v77
	v_pk_add_f32 v[78:79], v[78:79], s[22:23]
	v_pk_add_f32 v[80:81], v[80:81], s[22:23]
	v_pk_add_f32 v[74:75], v[74:75], s[22:23]
	v_pk_add_f32 v[76:77], v[76:77], s[22:23]
	v_rcp_f32_e32 v78, v78
	v_rcp_f32_e32 v79, v79
	v_rcp_f32_e32 v80, v80
	v_rcp_f32_e32 v81, v81
	v_rcp_f32_e32 v74, v74
	v_rcp_f32_e32 v75, v75
	v_rcp_f32_e32 v76, v76
	v_rcp_f32_e32 v77, v77
	v_pk_fma_f32 v[78:79], v[78:79], s[24:25], v[212:213]
	v_pk_fma_f32 v[80:81], v[80:81], s[24:25], v[212:213]
	v_pk_fma_f32 v[74:75], v[74:75], s[24:25], v[212:213]
	v_pk_fma_f32 v[76:77], v[76:77], s[24:25], v[212:213]
	v_cvt_pk_u8_f32 v186, v78, 0, 0
	v_cvt_pk_u8_f32 v186, v79, 1, v186
	v_cvt_pk_u8_f32 v186, v80, 2, v186
	v_cvt_pk_u8_f32 v186, v81, 3, v186
	v_cvt_pk_u8_f32 v187, v74, 0, 0
	v_cvt_pk_u8_f32 v187, v75, 1, v187
	v_cvt_pk_u8_f32 v187, v76, 2, v187
	v_cvt_pk_u8_f32 v187, v77, 3, v187
	global_store_dwordx2 v[184:185], v[186:187], off
	v_pk_mul_f32 v[70:71], v[70:71], s[100:101]
	v_pk_mul_f32 v[72:73], v[72:73], s[100:101]
	v_pk_mul_f32 v[66:67], v[66:67], s[100:101]
	v_pk_mul_f32 v[68:69], v[68:69], s[100:101]
	v_exp_f32_e32 v70, v70
	v_exp_f32_e32 v71, v71
	v_exp_f32_e32 v72, v72
	v_exp_f32_e32 v73, v73
	v_exp_f32_e32 v66, v66
	v_exp_f32_e32 v67, v67
	v_exp_f32_e32 v68, v68
	v_exp_f32_e32 v69, v69
	v_pk_add_f32 v[70:71], v[70:71], s[22:23]
	v_pk_add_f32 v[72:73], v[72:73], s[22:23]
	v_pk_add_f32 v[66:67], v[66:67], s[22:23]
	v_pk_add_f32 v[68:69], v[68:69], s[22:23]
	v_rcp_f32_e32 v70, v70
	v_rcp_f32_e32 v71, v71
	v_rcp_f32_e32 v72, v72
	v_rcp_f32_e32 v73, v73
	v_rcp_f32_e32 v66, v66
	v_rcp_f32_e32 v67, v67
	v_rcp_f32_e32 v68, v68
	v_rcp_f32_e32 v69, v69
	v_pk_fma_f32 v[70:71], v[70:71], s[24:25], v[212:213]
	v_pk_fma_f32 v[72:73], v[72:73], s[24:25], v[212:213]
	v_pk_fma_f32 v[66:67], v[66:67], s[24:25], v[212:213]
	v_pk_fma_f32 v[68:69], v[68:69], s[24:25], v[212:213]
	v_cvt_pk_u8_f32 v188, v70, 0, 0
	v_cvt_pk_u8_f32 v188, v71, 1, v188
	v_cvt_pk_u8_f32 v188, v72, 2, v188
	v_cvt_pk_u8_f32 v188, v73, 3, v188
	v_cvt_pk_u8_f32 v189, v66, 0, 0
	v_cvt_pk_u8_f32 v189, v67, 1, v189
	v_cvt_pk_u8_f32 v189, v68, 2, v189
	v_cvt_pk_u8_f32 v189, v69, 3, v189
	global_store_dwordx2 v[184:185], v[188:189], off offset:32
	s_mov_b32 s26, 0x18000
	v_lshl_add_u64 v[184:185], v[184:185], 0, s[26:27]
	v_pk_mul_f32 v[54:55], v[54:55], s[100:101]
	v_pk_mul_f32 v[56:57], v[56:57], s[100:101]
	v_pk_mul_f32 v[50:51], v[50:51], s[100:101]
	v_pk_mul_f32 v[52:53], v[52:53], s[100:101]
	v_exp_f32_e32 v54, v54
	v_exp_f32_e32 v55, v55
	v_exp_f32_e32 v56, v56
	v_exp_f32_e32 v57, v57
	v_exp_f32_e32 v50, v50
	v_exp_f32_e32 v51, v51
	v_exp_f32_e32 v52, v52
	v_exp_f32_e32 v53, v53
	v_pk_add_f32 v[54:55], v[54:55], s[22:23]
	v_pk_add_f32 v[56:57], v[56:57], s[22:23]
	v_pk_add_f32 v[50:51], v[50:51], s[22:23]
	v_pk_add_f32 v[52:53], v[52:53], s[22:23]
	v_rcp_f32_e32 v54, v54
	v_rcp_f32_e32 v55, v55
	v_rcp_f32_e32 v56, v56
	v_rcp_f32_e32 v57, v57
	v_rcp_f32_e32 v50, v50
	v_rcp_f32_e32 v51, v51
	v_rcp_f32_e32 v52, v52
	v_rcp_f32_e32 v53, v53
	v_pk_fma_f32 v[54:55], v[54:55], s[24:25], v[212:213]
	v_pk_fma_f32 v[56:57], v[56:57], s[24:25], v[212:213]
	v_pk_fma_f32 v[50:51], v[50:51], s[24:25], v[212:213]
	v_pk_fma_f32 v[52:53], v[52:53], s[24:25], v[212:213]
	v_cvt_pk_u8_f32 v186, v54, 0, 0
	v_cvt_pk_u8_f32 v186, v55, 1, v186
	v_cvt_pk_u8_f32 v186, v56, 2, v186
	v_cvt_pk_u8_f32 v186, v57, 3, v186
	v_cvt_pk_u8_f32 v187, v50, 0, 0
	v_cvt_pk_u8_f32 v187, v51, 1, v187
	v_cvt_pk_u8_f32 v187, v52, 2, v187
	v_cvt_pk_u8_f32 v187, v53, 3, v187
	global_store_dwordx2 v[184:185], v[186:187], off
	v_pk_mul_f32 v[38:39], v[38:39], s[100:101]
	v_pk_mul_f32 v[40:41], v[40:41], s[100:101]
	v_pk_mul_f32 v[34:35], v[34:35], s[100:101]
	v_pk_mul_f32 v[36:37], v[36:37], s[100:101]
	v_exp_f32_e32 v38, v38
	v_exp_f32_e32 v39, v39
	v_exp_f32_e32 v40, v40
	v_exp_f32_e32 v41, v41
	v_exp_f32_e32 v34, v34
	v_exp_f32_e32 v35, v35
	v_exp_f32_e32 v36, v36
	v_exp_f32_e32 v37, v37
	v_pk_add_f32 v[38:39], v[38:39], s[22:23]
	v_pk_add_f32 v[40:41], v[40:41], s[22:23]
	v_pk_add_f32 v[34:35], v[34:35], s[22:23]
	v_pk_add_f32 v[36:37], v[36:37], s[22:23]
	v_rcp_f32_e32 v38, v38
	v_rcp_f32_e32 v39, v39
	v_rcp_f32_e32 v40, v40
	v_rcp_f32_e32 v41, v41
	v_rcp_f32_e32 v34, v34
	v_rcp_f32_e32 v35, v35
	v_rcp_f32_e32 v36, v36
	v_rcp_f32_e32 v37, v37
	v_pk_fma_f32 v[38:39], v[38:39], s[24:25], v[212:213]
; __device__ __forceinline__ float fast_sigmoid(float v) { return __builtin_amdgcn_rcpf(1.0f + __builtin_amdgcn_exp2f(-v * LOG2E)); }
;     w = __builtin_amdgcn_cvt_pk_u8_f32(g[2] * 256.0f - 0.5f, 2, w); w = __builtin_amdgcn_cvt_pk_u8_f32(g[3] * 256.0f - 0.5f, 3, w); return w; }
;     __device__ __forceinline__ void operator()(Acc& acc, const Unit& u, int wr, int wc, int fr, int fq) const {
;     ...
;                     if (sig) {
; #pragma unroll
;                         for (int e = 0; e < 4; ++e) { v0[e] = fast_sigmoid(v0[e]); v1[e] = fast_sigmoid(v1[e]); }
;                         *(u32x2*)(rowp + (size_t)bj * sB) = (u32x2){pack_gate4(v0), pack_gate4(v1)}; }
	v_pk_fma_f32 v[40:41], v[40:41], s[24:25], v[212:213]
	v_pk_fma_f32 v[34:35], v[34:35], s[24:25], v[212:213]
	v_pk_fma_f32 v[36:37], v[36:37], s[24:25], v[212:213]
	v_cvt_pk_u8_f32 v188, v38, 0, 0
	v_cvt_pk_u8_f32 v188, v39, 1, v188
	v_cvt_pk_u8_f32 v188, v40, 2, v188
	v_cvt_pk_u8_f32 v188, v41, 3, v188
	v_cvt_pk_u8_f32 v189, v34, 0, 0
	v_cvt_pk_u8_f32 v189, v35, 1, v189
	v_cvt_pk_u8_f32 v189, v36, 2, v189
	v_cvt_pk_u8_f32 v189, v37, 3, v189
	global_store_dwordx2 v[184:185], v[188:189], off offset:32
	v_lshl_add_u64 v[184:185], v[184:185], 0, s[26:27]
	v_pk_mul_f32 v[30:31], v[30:31], s[100:101]
	v_pk_mul_f32 v[32:33], v[32:33], s[100:101]
	v_pk_mul_f32 v[26:27], v[26:27], s[100:101]
	v_pk_mul_f32 v[28:29], v[28:29], s[100:101]
	v_exp_f32_e32 v30, v30
	v_exp_f32_e32 v31, v31
	v_exp_f32_e32 v32, v32
	v_exp_f32_e32 v33, v33
	v_exp_f32_e32 v26, v26
	v_exp_f32_e32 v27, v27
	v_exp_f32_e32 v28, v28
	v_exp_f32_e32 v29, v29
	v_pk_add_f32 v[30:31], v[30:31], s[22:23]
	v_pk_add_f32 v[32:33], v[32:33], s[22:23]
	v_pk_add_f32 v[26:27], v[26:27], s[22:23]
	v_pk_add_f32 v[28:29], v[28:29], s[22:23]
	v_rcp_f32_e32 v30, v30
	v_rcp_f32_e32 v31, v31
	v_rcp_f32_e32 v32, v32
	v_rcp_f32_e32 v33, v33
	v_rcp_f32_e32 v26, v26
	v_rcp_f32_e32 v27, v27
	v_rcp_f32_e32 v28, v28
	v_rcp_f32_e32 v29, v29
	v_pk_fma_f32 v[30:31], v[30:31], s[24:25], v[212:213]
	v_pk_fma_f32 v[32:33], v[32:33], s[24:25], v[212:213]
	v_pk_fma_f32 v[26:27], v[26:27], s[24:25], v[212:213]
	v_pk_fma_f32 v[28:29], v[28:29], s[24:25], v[212:213]
	v_cvt_pk_u8_f32 v186, v30, 0, 0
	v_cvt_pk_u8_f32 v186, v31, 1, v186
	v_cvt_pk_u8_f32 v186, v32, 2, v186
	v_cvt_pk_u8_f32 v186, v33, 3, v186
	v_cvt_pk_u8_f32 v187, v26, 0, 0
	v_cvt_pk_u8_f32 v187, v27, 1, v187
	v_cvt_pk_u8_f32 v187, v28, 2, v187
	v_cvt_pk_u8_f32 v187, v29, 3, v187
	global_store_dwordx2 v[184:185], v[186:187], off
	v_pk_mul_f32 v[22:23], v[22:23], s[100:101]
	v_pk_mul_f32 v[24:25], v[24:25], s[100:101]
	v_pk_mul_f32 v[18:19], v[18:19], s[100:101]
	v_pk_mul_f32 v[20:21], v[20:21], s[100:101]
	v_exp_f32_e32 v22, v22
	v_exp_f32_e32 v23, v23
	v_exp_f32_e32 v24, v24
	v_exp_f32_e32 v25, v25
	v_exp_f32_e32 v18, v18
	v_exp_f32_e32 v19, v19
	v_exp_f32_e32 v20, v20
	v_exp_f32_e32 v21, v21
	v_pk_add_f32 v[22:23], v[22:23], s[22:23]
	v_pk_add_f32 v[24:25], v[24:25], s[22:23]
	v_pk_add_f32 v[18:19], v[18:19], s[22:23]
	v_pk_add_f32 v[20:21], v[20:21], s[22:23]
	v_rcp_f32_e32 v22, v22
	v_rcp_f32_e32 v23, v23
	v_rcp_f32_e32 v24, v24
	v_rcp_f32_e32 v25, v25
	v_rcp_f32_e32 v18, v18
	v_rcp_f32_e32 v19, v19
	v_rcp_f32_e32 v20, v20
	v_rcp_f32_e32 v21, v21
	v_pk_fma_f32 v[22:23], v[22:23], s[24:25], v[212:213]
	v_pk_fma_f32 v[24:25], v[24:25], s[24:25], v[212:213]
	v_pk_fma_f32 v[18:19], v[18:19], s[24:25], v[212:213]
	v_pk_fma_f32 v[20:21], v[20:21], s[24:25], v[212:213]
	v_cvt_pk_u8_f32 v188, v22, 0, 0
	v_cvt_pk_u8_f32 v188, v23, 1, v188
	v_cvt_pk_u8_f32 v188, v24, 2, v188
	v_cvt_pk_u8_f32 v188, v25, 3, v188
	v_cvt_pk_u8_f32 v189, v18, 0, 0
	v_cvt_pk_u8_f32 v189, v19, 1, v189
	v_cvt_pk_u8_f32 v189, v20, 2, v189
	v_cvt_pk_u8_f32 v189, v21, 3, v189
	global_store_dwordx2 v[184:185], v[188:189], off offset:32
	v_lshl_add_u64 v[184:185], v[184:185], 0, s[26:27]
	v_pk_mul_f32 v[14:15], v[14:15], s[100:101]
	v_pk_mul_f32 v[16:17], v[16:17], s[100:101]
	v_pk_mul_f32 v[10:11], v[10:11], s[100:101]
	v_pk_mul_f32 v[12:13], v[12:13], s[100:101]
	v_exp_f32_e32 v14, v14
	v_exp_f32_e32 v15, v15
	v_exp_f32_e32 v16, v16
	v_exp_f32_e32 v17, v17
	v_exp_f32_e32 v10, v10
	v_exp_f32_e32 v11, v11
	v_exp_f32_e32 v12, v12
	v_exp_f32_e32 v13, v13
	v_pk_add_f32 v[14:15], v[14:15], s[22:23]
	v_pk_add_f32 v[16:17], v[16:17], s[22:23]
	v_pk_add_f32 v[10:11], v[10:11], s[22:23]
	v_pk_add_f32 v[12:13], v[12:13], s[22:23]
	v_rcp_f32_e32 v14, v14
	v_rcp_f32_e32 v15, v15
	v_rcp_f32_e32 v16, v16
	v_rcp_f32_e32 v17, v17
	v_rcp_f32_e32 v10, v10
	v_rcp_f32_e32 v11, v11
	v_rcp_f32_e32 v12, v12
	v_rcp_f32_e32 v13, v13
	v_pk_fma_f32 v[14:15], v[14:15], s[24:25], v[212:213]
	v_pk_fma_f32 v[16:17], v[16:17], s[24:25], v[212:213]
	v_pk_fma_f32 v[10:11], v[10:11], s[24:25], v[212:213]
	v_pk_fma_f32 v[12:13], v[12:13], s[24:25], v[212:213]
	v_cvt_pk_u8_f32 v186, v14, 0, 0
	v_cvt_pk_u8_f32 v186, v15, 1, v186
	v_cvt_pk_u8_f32 v186, v16, 2, v186
	v_cvt_pk_u8_f32 v186, v17, 3, v186
	v_cvt_pk_u8_f32 v187, v10, 0, 0
	v_cvt_pk_u8_f32 v187, v11, 1, v187
	v_cvt_pk_u8_f32 v187, v12, 2, v187
	v_cvt_pk_u8_f32 v187, v13, 3, v187
	global_store_dwordx2 v[184:185], v[186:187], off
	v_pk_mul_f32 v[6:7], v[6:7], s[100:101]
	v_pk_mul_f32 v[8:9], v[8:9], s[100:101]
	v_pk_mul_f32 v[2:3], v[2:3], s[100:101]
	v_pk_mul_f32 v[4:5], v[4:5], s[100:101]
	v_exp_f32_e32 v6, v6
	v_exp_f32_e32 v7, v7
	v_exp_f32_e32 v8, v8
	v_exp_f32_e32 v9, v9
	v_exp_f32_e32 v2, v2
	v_exp_f32_e32 v3, v3
	v_exp_f32_e32 v4, v4
	v_exp_f32_e32 v5, v5
	v_pk_add_f32 v[6:7], v[6:7], s[22:23]
	v_pk_add_f32 v[8:9], v[8:9], s[22:23]
	v_pk_add_f32 v[2:3], v[2:3], s[22:23]
	v_pk_add_f32 v[4:5], v[4:5], s[22:23]
	v_rcp_f32_e32 v6, v6
	v_rcp_f32_e32 v7, v7
	v_rcp_f32_e32 v8, v8
	v_rcp_f32_e32 v9, v9
	v_rcp_f32_e32 v2, v2
	v_rcp_f32_e32 v3, v3
	v_rcp_f32_e32 v4, v4
	v_rcp_f32_e32 v5, v5
	v_pk_fma_f32 v[6:7], v[6:7], s[24:25], v[212:213]
	v_pk_fma_f32 v[8:9], v[8:9], s[24:25], v[212:213]
	v_pk_fma_f32 v[2:3], v[2:3], s[24:25], v[212:213]
	v_pk_fma_f32 v[4:5], v[4:5], s[24:25], v[212:213]
	v_cvt_pk_u8_f32 v188, v6, 0, 0
	v_cvt_pk_u8_f32 v188, v7, 1, v188
	v_cvt_pk_u8_f32 v188, v8, 2, v188
	v_cvt_pk_u8_f32 v188, v9, 3, v188
	v_cvt_pk_u8_f32 v189, v2, 0, 0
	v_cvt_pk_u8_f32 v189, v3, 1, v189
	v_cvt_pk_u8_f32 v189, v4, 2, v189
	v_cvt_pk_u8_f32 v189, v5, 3, v189
	global_store_dwordx2 v[184:185], v[188:189], off offset:32
	s_andn2_b64 vcc, exec, s[0:1]
	s_mov_b64 s[0:1], -1
	s_cbranch_vccnz .LBB0_255
	s_branch .LBB0_338
